# HGRN mode0 chunk: all 16 f-logit loads in one batch + next-chunk L2 touches
# speedup vs baseline: 1.0121x; 1.0039x over previous
; #define LAS __attribute__((address_space(3)))
; __device__ __forceinline__ float bf2f(unsigned short h) { return __uint_as_float(((unsigned)h) << 16); }
; __device__ __forceinline__ float sigmoidf_(float x) { return __builtin_amdgcn_rcpf(1.f + __expf(-x)); }
; template <int MODE> __device__ __forceinline__ void hgrn_unit(LAS unsigned char* lds, const Params& P, int unit) {
;     ...
;     for (int c = 0; c < 4; ++c) {
;         const int t0 = tok0 + 64 * c;
; #pragma unroll
;         for (int i = 0; i < 2; ++i) { const int ch = tid + 512 * i, r = ch >> 4, cc = ch & 15;
;             *(LAS u32x4*)(T3 + r * TS + cc * 16) = *(const u32x4*)(ZA + (size_t)(t0 + r) * 4096 + 2048 + h * 128 + cc * 8); }
;         float bb[16], kk[16], qq[16];
;         float run = 0.f;
; #pragma unroll
;         for (int i = 0; i < 16; ++i) {
;             const size_t ro = (size_t)(t0 + 16 * g + i) * 4096 + h * 128 + k;
;             const float x = bf2f(ZA[ro + 1024]);
;             const float f = lb + (1.f - lb) * sigmoidf_(x);
;             run += __logf(f); bb[i] = run; kk[i] = 1.f - f;
;             if (MODE == 1) qq[i] = bf2f(ZA[ro]);
;         }
.LBB0_599:
	v_add_u32_e32 v36, s7, v50
	v_ashrrev_i32_e32 v37, 31, v36
	v_lshlrev_b64 v[36:37], 13, v[36:37]
	v_lshl_add_u64 v[36:37], s[72:73], 0, v[36:37]
	v_lshl_add_u64 v[36:37], v[36:37], 0, s[22:23]
	v_lshl_add_u64 v[36:37], v[36:37], 0, v[180:181]
	v_add_co_u32_e32 v38, vcc, s78, v36
	v_add_u32_e32 v36, s7, v49
	s_nop 0
	v_addc_co_u32_e32 v39, vcc, 0, v37, vcc
	v_ashrrev_i32_e32 v37, 31, v36
	v_lshlrev_b64 v[36:37], 13, v[36:37]
	v_lshl_add_u64 v[36:37], s[72:73], 0, v[36:37]
	v_lshl_add_u64 v[36:37], v[36:37], 0, s[22:23]
	v_lshl_add_u64 v[56:57], v[36:37], 0, v[180:181]
	v_add_u32_e32 v36, s7, v48
	v_ashrrev_i32_e32 v37, 31, v36
	v_add_u32_e32 v60, 1, v36
	v_add_u32_e32 v62, 2, v36
	v_lshlrev_b64 v[58:59], 13, v[36:37]
	v_ashrrev_i32_e32 v61, 31, v60
	v_ashrrev_i32_e32 v63, 31, v62
	v_lshl_add_u64 v[58:59], v[34:35], 0, v[58:59]
	v_lshlrev_b64 v[60:61], 13, v[60:61]
	v_lshlrev_b64 v[62:63], 13, v[62:63]
	v_lshl_add_u64 v[60:61], v[34:35], 0, v[60:61]
	v_lshl_add_u64 v[62:63], v[34:35], 0, v[62:63]
	global_load_ushort v37, v[58:59], off offset:2048
	global_load_ushort v70, v[60:61], off offset:2048
	global_load_ushort v71, v[62:63], off offset:2048
	v_add_co_u32_e32 v60, vcc, s78, v56
	v_add_u32_e32 v64, 5, v36
	s_nop 0
	v_addc_co_u32_e32 v61, vcc, 0, v57, vcc
	v_add_co_u32_e32 v142, vcc, 0x80000, v38
	s_nop 1
	v_addc_co_u32_e32 v143, vcc, 0, v39, vcc
	v_add_co_u32_e32 v144, vcc, 0x80000, v60
	s_nop 1
	v_addc_co_u32_e32 v145, vcc, 0, v61, vcc
	global_load_dwordx4 v[56:59], v[38:39], off
	s_nop 0
	global_load_dwordx4 v[60:63], v[60:61], off
	v_add_u32_e32 v38, 3, v36
	v_ashrrev_i32_e32 v39, 31, v38
	v_lshlrev_b64 v[38:39], 13, v[38:39]
	v_lshl_add_u64 v[38:39], v[34:35], 0, v[38:39]
	global_load_ushort v72, v[38:39], off offset:2048
	v_add_u32_e32 v38, 4, v36
	v_ashrrev_i32_e32 v39, 31, v38
	v_lshlrev_b64 v[38:39], 13, v[38:39]
	v_lshl_add_u64 v[38:39], v[34:35], 0, v[38:39]
	global_load_ushort v73, v[38:39], off offset:2048
	v_add_u32_e32 v66, 6, v36
	v_add_u32_e32 v68, 7, v36
	v_ashrrev_i32_e32 v65, 31, v64
	v_ashrrev_i32_e32 v67, 31, v66
	v_ashrrev_i32_e32 v69, 31, v68
	v_lshlrev_b64 v[38:39], 13, v[64:65]
	v_lshlrev_b64 v[64:65], 13, v[66:67]
	v_lshlrev_b64 v[66:67], 13, v[68:69]
	v_lshl_add_u64 v[38:39], v[34:35], 0, v[38:39]
	v_lshl_add_u64 v[64:65], v[34:35], 0, v[64:65]
	v_lshl_add_u64 v[66:67], v[34:35], 0, v[66:67]
	global_load_ushort v38, v[38:39], off offset:2048
	s_nop 0
	global_load_ushort v68, v[64:65], off offset:2048
	global_load_ushort v69, v[66:67], off offset:2048
	v_add_u32_e32 v128, 8, v36
	v_ashrrev_i32_e32 v129, 31, v128
	v_lshlrev_b64 v[128:129], 13, v[128:129]
	v_lshl_add_u64 v[128:129], v[34:35], 0, v[128:129]
	global_load_ushort v130, v[128:129], off offset:2048
	v_add_u32_e32 v128, 9, v36
	v_ashrrev_i32_e32 v129, 31, v128
	v_lshlrev_b64 v[128:129], 13, v[128:129]
	v_lshl_add_u64 v[128:129], v[34:35], 0, v[128:129]
	global_load_ushort v131, v[128:129], off offset:2048
	v_add_u32_e32 v128, 10, v36
	v_ashrrev_i32_e32 v129, 31, v128
	v_lshlrev_b64 v[128:129], 13, v[128:129]
	v_lshl_add_u64 v[128:129], v[34:35], 0, v[128:129]
	global_load_ushort v132, v[128:129], off offset:2048
	v_add_u32_e32 v128, 11, v36
	v_ashrrev_i32_e32 v129, 31, v128
	v_lshlrev_b64 v[128:129], 13, v[128:129]
	v_lshl_add_u64 v[128:129], v[34:35], 0, v[128:129]
	global_load_ushort v133, v[128:129], off offset:2048
	v_add_u32_e32 v128, 12, v36
	v_ashrrev_i32_e32 v129, 31, v128
	v_lshlrev_b64 v[128:129], 13, v[128:129]
	v_lshl_add_u64 v[128:129], v[34:35], 0, v[128:129]
	global_load_ushort v134, v[128:129], off offset:2048
	v_add_u32_e32 v128, 13, v36
	v_ashrrev_i32_e32 v129, 31, v128
	v_lshlrev_b64 v[128:129], 13, v[128:129]
	v_lshl_add_u64 v[128:129], v[34:35], 0, v[128:129]
	global_load_ushort v135, v[128:129], off offset:2048
	v_add_u32_e32 v128, 14, v36
	v_ashrrev_i32_e32 v129, 31, v128
	v_lshlrev_b64 v[128:129], 13, v[128:129]
	v_lshl_add_u64 v[128:129], v[34:35], 0, v[128:129]
	global_load_ushort v136, v[128:129], off offset:2048
	v_add_u32_e32 v128, 15, v36
	v_ashrrev_i32_e32 v129, 31, v128
	v_lshlrev_b64 v[128:129], 13, v[128:129]
	v_lshl_add_u64 v[128:129], v[34:35], 0, v[128:129]
	global_load_ushort v137, v[128:129], off offset:2048
	v_and_b32_e32 v128, 15, v208
	v_add3_u32 v128, v36, v128, 64
	v_ashrrev_i32_e32 v129, 31, v128
	v_lshlrev_b64 v[128:129], 13, v[128:129]
	v_lshl_add_u64 v[128:129], v[34:35], 0, v[128:129]
	global_load_ushort v138, v[128:129], off offset:2048
	global_load_dword v139, v[142:143], off
	global_load_dword v140, v[144:145], off
	v_add_u32_e32 v74, 14, v36
	v_ashrrev_i32_e32 v75, 31, v74
	v_lshlrev_b64 v[74:75], 13, v[74:75]
	v_lshl_add_u64 v[74:75], v[34:35], 0, v[74:75]
	s_waitcnt vmcnt(17)
	ds_write_b128 v45, v[56:59] offset:36864
	s_waitcnt vmcnt(16)
	ds_write_b128 v46, v[60:63] offset:36864
	v_lshlrev_b32_e32 v37, 16, v37
	v_mul_f32_e32 v37, 0xbfb8aa3b, v37
	v_lshlrev_b32_e32 v39, 16, v70
	v_exp_f32_e32 v37, v37
	v_mul_f32_e32 v39, 0xbfb8aa3b, v39
	v_lshlrev_b32_e32 v64, 16, v71
	v_exp_f32_e32 v39, v39
	v_mul_f32_e32 v64, 0xbfb8aa3b, v64
	v_exp_f32_e32 v56, v64
	v_add_f32_e32 v37, 1.0, v37
	v_rcp_f32_e32 v37, v37
	v_add_f32_e32 v39, 1.0, v39
	v_rcp_f32_e32 v39, v39
	v_add_f32_e32 v56, 1.0, v56
	v_rcp_f32_e32 v58, v56
	v_fma_f32 v56, v55, v37, v54
	v_cmp_gt_f32_e32 vcc, s71, v56
	v_fma_f32 v57, v55, v39, v54
	v_fma_f32 v58, v55, v58, v54
	v_cndmask_b32_e64 v37, 0, 32, vcc
	v_ldexp_f32 v37, v56, v37
	v_cndmask_b32_e32 v39, 0, v213, vcc
	v_cmp_gt_f32_e32 vcc, s71, v57
	v_log_f32_e32 v37, v37
	v_cmp_gt_f32_e64 s[0:1], s71, v58
	v_cndmask_b32_e64 v59, 0, 32, vcc
	v_ldexp_f32 v59, v57, v59
	v_cndmask_b32_e64 v60, 0, 32, s[0:1]
	v_log_f32_e32 v59, v59
	v_ldexp_f32 v60, v58, v60
	v_log_f32_e32 v61, v60
	v_mul_f32_e32 v60, 0x3f317217, v37
	v_fma_f32 v60, v37, s95, -v60
	v_mul_f32_e32 v62, 0x3f317217, v59
	v_fmac_f32_e32 v60, 0x3377d1cf, v37
	v_fma_f32 v62, v59, s95, -v62
	v_fmac_f32_e32 v60, 0x3f317217, v37
	v_cmp_lt_f32_e64 s[46:47], |v37|, s88
	v_fmac_f32_e32 v62, 0x3377d1cf, v59
	v_fmac_f32_e32 v62, 0x3f317217, v59
	v_cndmask_b32_e64 v37, v37, v60, s[46:47]
	v_sub_f32_e32 v37, v37, v39
	v_cmp_lt_f32_e64 s[46:47], |v59|, s88
	s_waitcnt vmcnt(13)
; __device__ __forceinline__ float bf2f(unsigned short h) { return __uint_as_float(((unsigned)h) << 16); }
; __device__ __forceinline__ float sigmoidf_(float x) { return __builtin_amdgcn_rcpf(1.f + __expf(-x)); }
; template <int MODE> __device__ __forceinline__ void hgrn_unit(LAS unsigned char* lds, const Params& P, int unit) {
;     ...
; #pragma unroll
;         for (int i = 0; i < 16; ++i) {
;             const size_t ro = (size_t)(t0 + 16 * g + i) * 4096 + h * 128 + k;
;             const float x = bf2f(ZA[ro + 1024]);
;             const float f = lb + (1.f - lb) * sigmoidf_(x);
;             run += __logf(f); bb[i] = run; kk[i] = 1.f - f;
;             if (MODE == 1) qq[i] = bf2f(ZA[ro]);
;         }
	v_lshlrev_b32_e32 v38, 16, v38
	v_mul_f32_e32 v38, 0xbfb8aa3b, v38
	v_cndmask_b32_e64 v39, v59, v62, s[46:47]
	v_add_f32_e32 v59, 0, v37
	v_cndmask_b32_e32 v37, 0, v213, vcc
	v_sub_f32_e32 v37, v39, v37
	v_lshlrev_b32_e32 v39, 16, v72
	v_mul_f32_e32 v39, 0xbfb8aa3b, v39
	v_exp_f32_e32 v39, v39
	v_add_f32_e32 v60, v59, v37
	v_mul_f32_e32 v37, 0x3f317217, v61
	v_fma_f32 v37, v61, s95, -v37
	v_add_f32_e32 v39, 1.0, v39
	v_rcp_f32_e32 v39, v39
	v_fmac_f32_e32 v37, 0x3377d1cf, v61
	v_fmac_f32_e32 v37, 0x3f317217, v61
	v_cmp_lt_f32_e64 vcc, |v61|, s88
	v_fma_f32 v62, v55, v39, v54
	v_lshlrev_b32_e32 v39, 16, v73
	v_cndmask_b32_e32 v37, v61, v37, vcc
	v_cndmask_b32_e64 v61, 0, v213, s[0:1]
	v_sub_f32_e32 v37, v37, v61
	v_cmp_gt_f32_e32 vcc, s71, v62
	v_mul_f32_e32 v39, 0xbfb8aa3b, v39
	v_add_f32_e32 v61, v60, v37
	v_cndmask_b32_e64 v37, 0, 32, vcc
	v_exp_f32_e32 v39, v39
	v_ldexp_f32 v37, v62, v37
	v_log_f32_e32 v37, v37
	v_exp_f32_e32 v38, v38
	v_add_f32_e32 v39, 1.0, v39
	v_rcp_f32_e32 v39, v39
	v_mul_f32_e32 v63, 0x3f317217, v37
	v_fma_f32 v63, v37, s95, -v63
	v_fmac_f32_e32 v63, 0x3377d1cf, v37
	v_fmac_f32_e32 v63, 0x3f317217, v37
	v_cmp_lt_f32_e64 s[0:1], |v37|, s88
	v_fma_f32 v64, v55, v39, v54
	v_add_f32_e32 v38, 1.0, v38
	v_cndmask_b32_e64 v37, v37, v63, s[0:1]
	v_cmp_gt_f32_e64 s[0:1], s71, v64
	v_cndmask_b32_e32 v63, 0, v213, vcc
	v_sub_f32_e32 v37, v37, v63
	v_cndmask_b32_e64 v39, 0, 32, s[0:1]
	v_ldexp_f32 v39, v64, v39
	v_log_f32_e32 v39, v39
	v_add_f32_e32 v63, v61, v37
	v_rcp_f32_e32 v38, v38
	v_add_u32_e32 v72, 13, v36
	v_mul_f32_e32 v37, 0x3f317217, v39
	v_fma_f32 v37, v39, s95, -v37
	v_fmac_f32_e32 v37, 0x3377d1cf, v39
	v_fmac_f32_e32 v37, 0x3f317217, v39
	v_cmp_lt_f32_e64 vcc, |v39|, s88
	v_fma_f32 v66, v55, v38, v54
	v_add_u32_e32 v38, 8, v36
	v_cndmask_b32_e32 v37, v39, v37, vcc
	v_cndmask_b32_e64 v39, 0, v213, s[0:1]
	v_sub_f32_e32 v37, v37, v39
	v_ashrrev_i32_e32 v39, 31, v38
	v_lshlrev_b64 v[38:39], 13, v[38:39]
	v_lshl_add_u64 v[38:39], v[34:35], 0, v[38:39]
	v_cmp_gt_f32_e32 vcc, s71, v66
	s_waitcnt vmcnt(12)
	v_lshlrev_b32_e32 v38, 16, v68
	v_add_f32_e32 v65, v63, v37
	v_cndmask_b32_e64 v37, 0, 32, vcc
	v_mul_f32_e32 v38, 0xbfb8aa3b, v38
	v_ldexp_f32 v37, v66, v37
	v_exp_f32_e32 v38, v38
	v_log_f32_e32 v37, v37
	v_ashrrev_i32_e32 v73, 31, v72
	v_lshlrev_b64 v[72:73], 13, v[72:73]
	v_add_f32_e32 v38, 1.0, v38
	v_mul_f32_e32 v39, 0x3f317217, v37
	v_rcp_f32_e32 v68, v38
	v_add_u32_e32 v38, 9, v36
	v_fma_f32 v67, v37, s95, -v39
	v_ashrrev_i32_e32 v39, 31, v38
	v_lshlrev_b64 v[38:39], 13, v[38:39]
	v_lshl_add_u64 v[38:39], v[34:35], 0, v[38:39]
	v_fmac_f32_e32 v67, 0x3377d1cf, v37
	v_fmac_f32_e32 v67, 0x3f317217, v37
	v_cmp_lt_f32_e64 s[0:1], |v37|, s88
	v_fma_f32 v68, v55, v68, v54
	v_lshl_add_u64 v[72:73], v[34:35], 0, v[72:73]
	v_cndmask_b32_e64 v37, v37, v67, s[0:1]
	v_cmp_gt_f32_e64 s[0:1], s71, v68
	s_nop 1
	v_cndmask_b32_e64 v38, 0, 32, s[0:1]
	v_ldexp_f32 v38, v68, v38
	v_log_f32_e32 v70, v38
	v_cndmask_b32_e32 v38, 0, v213, vcc
	v_sub_f32_e32 v37, v37, v38
	s_waitcnt vmcnt(11)
	v_lshlrev_b32_e32 v38, 16, v69
	v_mul_f32_e32 v38, 0xbfb8aa3b, v38
	v_exp_f32_e32 v69, v38
	v_add_u32_e32 v38, 10, v36
	v_ashrrev_i32_e32 v39, 31, v38
	v_lshlrev_b64 v[38:39], 13, v[38:39]
	v_lshl_add_u64 v[38:39], v[34:35], 0, v[38:39]
	v_add_f32_e32 v38, 1.0, v69
	v_rcp_f32_e32 v38, v38
	v_add_f32_e32 v67, v65, v37
	v_mul_f32_e32 v37, 0x3f317217, v70
	v_fma_f32 v37, v70, s95, -v37
	v_fmac_f32_e32 v37, 0x3377d1cf, v70
	v_fmac_f32_e32 v37, 0x3f317217, v70
	v_cmp_lt_f32_e64 vcc, |v70|, s88
	v_fma_f32 v69, v55, v38, v54
	s_nop 0
	v_cndmask_b32_e32 v37, v70, v37, vcc
	v_cmp_gt_f32_e32 vcc, s71, v69
	v_cndmask_b32_e64 v70, 0, v213, s[0:1]
	v_sub_f32_e32 v37, v37, v70
	v_cndmask_b32_e64 v38, 0, 32, vcc
	v_ldexp_f32 v38, v69, v38
	v_log_f32_e32 v78, v38
	v_add_u32_e32 v38, 11, v36
	v_ashrrev_i32_e32 v39, 31, v38
	v_lshlrev_b64 v[38:39], 13, v[38:39]
	v_lshl_add_u64 v[38:39], v[34:35], 0, v[38:39]
	v_add_f32_e32 v70, v67, v37
	v_mul_f32_e32 v37, 0x3f317217, v78
	v_add_u32_e32 v38, 12, v36
	v_add_u32_e32 v36, 15, v36
	v_fma_f32 v80, v78, s95, -v37
	v_ashrrev_i32_e32 v39, 31, v38
	v_ashrrev_i32_e32 v37, 31, v36
	v_lshlrev_b64 v[38:39], 13, v[38:39]
	v_lshlrev_b64 v[36:37], 13, v[36:37]
	v_lshl_add_u64 v[38:39], v[34:35], 0, v[38:39]
	v_lshl_add_u64 v[36:37], v[34:35], 0, v[36:37]
	s_nop 0
	s_nop 0
	v_fmac_f32_e32 v80, 0x3377d1cf, v78
	v_fmac_f32_e32 v80, 0x3f317217, v78
	v_cmp_lt_f32_e64 s[0:1], |v78|, s88
	v_cndmask_b32_e32 v72, 0, v213, vcc
	s_waitcnt vmcnt(10)
	v_lshlrev_b32_e32 v37, 16, v130
	v_mul_f32_e32 v37, 0xbfb8aa3b, v37
	v_exp_f32_e32 v37, v37
	v_cndmask_b32_e64 v71, v78, v80, s[0:1]
	v_sub_f32_e32 v71, v71, v72
	v_add_f32_e32 v71, v70, v71
	v_add_f32_e32 v37, 1.0, v37
	v_rcp_f32_e32 v37, v37
	s_waitcnt vmcnt(9)
	v_lshlrev_b32_e32 v73, 16, v131
	v_fma_f32 v72, v55, v37, v54
	v_cmp_gt_f32_e32 vcc, s71, v72
	v_mul_f32_e32 v73, 0xbfb8aa3b, v73
	v_exp_f32_e32 v73, v73
	v_cndmask_b32_e64 v37, 0, 32, vcc
	v_ldexp_f32 v37, v72, v37
	v_log_f32_e32 v37, v37
	v_add_f32_e32 v73, 1.0, v73
	v_rcp_f32_e32 v73, v73
	v_mul_f32_e32 v74, 0x3f317217, v37
	v_fma_f32 v74, v37, s95, -v74
	v_fmac_f32_e32 v74, 0x3377d1cf, v37
	v_fmac_f32_e32 v74, 0x3f317217, v37
	v_cmp_lt_f32_e64 s[0:1], |v37|, s88
	s_waitcnt vmcnt(8)
; __device__ __forceinline__ float bf2f(unsigned short h) { return __uint_as_float(((unsigned)h) << 16); }
; __device__ __forceinline__ float sigmoidf_(float x) { return __builtin_amdgcn_rcpf(1.f + __expf(-x)); }
; template <int MODE> __device__ __forceinline__ void hgrn_unit(LAS unsigned char* lds, const Params& P, int unit) {
;     ...
; #pragma unroll
;         for (int i = 0; i < 16; ++i) {
;             const size_t ro = (size_t)(t0 + 16 * g + i) * 4096 + h * 128 + k;
;             const float x = bf2f(ZA[ro + 1024]);
;             const float f = lb + (1.f - lb) * sigmoidf_(x);
;             run += __logf(f); bb[i] = run; kk[i] = 1.f - f;
;             if (MODE == 1) qq[i] = bf2f(ZA[ro]);
;         }
;         SEG[g * 128 + k] = run;
;         __syncthreads();
;         const float s0 = SEG[k], s1 = SEG[128 + k], s2 = SEG[256 + k], s3 = SEG[384 + k];
;         const float pre = (g > 0 ? s0 : 0.f) + (g > 1 ? s1 : 0.f) + (g > 2 ? s2 : 0.f);
;         const float btot = (s0 + s1) + (s2 + s3), ref = s0 + s1;
;         if (g == 0) { const float e = __expf(btot); DL[k] = e; Dacc *= e; }
	v_lshlrev_b32_e32 v76, 16, v132
	v_cndmask_b32_e64 v37, v37, v74, s[0:1]
	v_fma_f32 v74, v55, v73, v54
	v_cmp_gt_f32_e64 s[0:1], s71, v74
	v_mul_f32_e32 v76, 0xbfb8aa3b, v76
	v_exp_f32_e32 v76, v76
	v_cndmask_b32_e64 v73, 0, 32, s[0:1]
	v_ldexp_f32 v73, v74, v73
	v_log_f32_e32 v75, v73
	v_cndmask_b32_e32 v73, 0, v213, vcc
	v_sub_f32_e32 v37, v37, v73
	v_add_f32_e32 v73, v71, v37
	v_mul_f32_e32 v37, 0x3f317217, v75
	v_fma_f32 v37, v75, s95, -v37
	v_fmac_f32_e32 v37, 0x3377d1cf, v75
	v_fmac_f32_e32 v37, 0x3f317217, v75
	v_cmp_lt_f32_e64 vcc, |v75|, s88
	s_waitcnt vmcnt(7)
	v_lshlrev_b32_e32 v77, 16, v133
	v_cndmask_b32_e32 v37, v75, v37, vcc
	v_add_f32_e32 v75, 1.0, v76
	v_rcp_f32_e32 v76, v75
	v_cndmask_b32_e64 v75, 0, v213, s[0:1]
	v_sub_f32_e32 v37, v37, v75
	v_add_f32_e32 v75, v73, v37
	v_fma_f32 v76, v55, v76, v54
	v_cmp_gt_f32_e32 vcc, s71, v76
	v_mul_f32_e32 v77, 0xbfb8aa3b, v77
	v_exp_f32_e32 v77, v77
	v_cndmask_b32_e64 v37, 0, 32, vcc
	v_ldexp_f32 v37, v76, v37
	v_log_f32_e32 v37, v37
	v_add_f32_e32 v77, 1.0, v77
	v_rcp_f32_e32 v77, v77
	s_waitcnt vmcnt(6)
	v_lshlrev_b32_e32 v38, 16, v134
	v_mul_f32_e32 v78, 0x3f317217, v37
	v_fma_f32 v78, v37, s95, -v78
	v_fmac_f32_e32 v78, 0x3377d1cf, v37
	v_fmac_f32_e32 v78, 0x3f317217, v37
	v_cmp_lt_f32_e64 s[0:1], |v37|, s88
	v_mul_f32_e32 v38, 0xbfb8aa3b, v38
	v_exp_f32_e32 v38, v38
	v_cndmask_b32_e64 v37, v37, v78, s[0:1]
	v_fma_f32 v78, v55, v77, v54
	v_cmp_gt_f32_e64 s[0:1], s71, v78
	v_add_f32_e32 v38, 1.0, v38
	v_rcp_f32_e32 v38, v38
	v_cndmask_b32_e64 v77, 0, 32, s[0:1]
	v_ldexp_f32 v77, v78, v77
	v_log_f32_e32 v79, v77
	v_cndmask_b32_e32 v77, 0, v213, vcc
	v_sub_f32_e32 v37, v37, v77
	v_add_f32_e32 v77, v75, v37
	v_mul_f32_e32 v37, 0x3f317217, v79
	v_fma_f32 v37, v79, s95, -v37
	v_fmac_f32_e32 v37, 0x3377d1cf, v79
	v_fmac_f32_e32 v37, 0x3f317217, v79
	v_cmp_lt_f32_e64 vcc, |v79|, s88
	v_fma_f32 v80, v55, v38, v54
	s_waitcnt vmcnt(5)
	v_lshlrev_b32_e32 v38, 16, v135
	v_cndmask_b32_e32 v37, v79, v37, vcc
	v_cndmask_b32_e64 v79, 0, v213, s[0:1]
	v_sub_f32_e32 v37, v37, v79
	v_cmp_gt_f32_e32 vcc, s71, v80
	v_mul_f32_e32 v38, 0xbfb8aa3b, v38
	v_add_f32_e32 v79, v77, v37
	v_cndmask_b32_e64 v37, 0, 32, vcc
	v_exp_f32_e32 v38, v38
	v_ldexp_f32 v37, v80, v37
	v_log_f32_e32 v37, v37
	s_waitcnt vmcnt(3)
	v_lshlrev_b32_e32 v36, 16, v137
	v_add_f32_e32 v38, 1.0, v38
	v_rcp_f32_e32 v38, v38
	v_mul_f32_e32 v39, 0x3f317217, v37
	v_fma_f32 v39, v37, s95, -v39
	v_fmac_f32_e32 v39, 0x3377d1cf, v37
	v_fmac_f32_e32 v39, 0x3f317217, v37
	v_cmp_lt_f32_e64 s[0:1], |v37|, s88
	v_fma_f32 v82, v55, v38, v54
	v_mul_f32_e32 v36, 0xbfb8aa3b, v36
	v_cndmask_b32_e64 v37, v37, v39, s[0:1]
	v_cmp_gt_f32_e64 s[0:1], s71, v82
	v_cndmask_b32_e32 v39, 0, v213, vcc
	v_sub_f32_e32 v37, v37, v39
	v_cndmask_b32_e64 v38, 0, 32, s[0:1]
	v_ldexp_f32 v38, v82, v38
	v_log_f32_e32 v38, v38
	v_lshlrev_b32_e32 v39, 16, v136
	v_mul_f32_e32 v39, 0xbfb8aa3b, v39
	v_add_f32_e32 v81, v79, v37
	v_mul_f32_e32 v37, 0x3f317217, v38
	v_exp_f32_e32 v39, v39
	v_fma_f32 v37, v38, s95, -v37
	v_fmac_f32_e32 v37, 0x3377d1cf, v38
	v_fmac_f32_e32 v37, 0x3f317217, v38
	v_cmp_lt_f32_e64 vcc, |v38|, s88
	v_exp_f32_e32 v36, v36
	s_nop 0
	v_cndmask_b32_e32 v37, v38, v37, vcc
	v_add_f32_e32 v38, 1.0, v39
	v_rcp_f32_e32 v38, v38
	v_cndmask_b32_e64 v39, 0, v213, s[0:1]
	v_sub_f32_e32 v37, v37, v39
	v_add_f32_e32 v83, v81, v37
	v_fma_f32 v84, v55, v38, v54
	v_cmp_gt_f32_e32 vcc, s71, v84
	v_add_f32_e32 v36, 1.0, v36
	v_rcp_f32_e32 v36, v36
	v_cndmask_b32_e64 v37, 0, 32, vcc
	v_ldexp_f32 v37, v84, v37
	v_log_f32_e32 v37, v37
	v_fma_f32 v87, v55, v36, v54
	v_mul_f32_e32 v38, 0x3f317217, v37
	v_fma_f32 v38, v37, s95, -v38
	v_fmac_f32_e32 v38, 0x3377d1cf, v37
	v_fmac_f32_e32 v38, 0x3f317217, v37
	v_cmp_lt_f32_e64 s[0:1], |v37|, s88
	s_nop 1
	v_cndmask_b32_e64 v37, v37, v38, s[0:1]
	v_cmp_gt_f32_e64 s[0:1], s71, v87
	v_cndmask_b32_e32 v38, 0, v213, vcc
	v_sub_f32_e32 v37, v37, v38
	v_cndmask_b32_e64 v36, 0, 32, s[0:1]
	v_ldexp_f32 v36, v87, v36
	v_log_f32_e32 v36, v36
	v_add_f32_e32 v85, v83, v37
	v_mul_f32_e32 v37, 0x3f317217, v36
	v_fma_f32 v37, v36, s95, -v37
	v_fmac_f32_e32 v37, 0x3377d1cf, v36
	v_fmac_f32_e32 v37, 0x3f317217, v36
	v_cmp_lt_f32_e64 vcc, |v36|, s88
	s_nop 1
	v_cndmask_b32_e32 v36, v36, v37, vcc
	v_cndmask_b32_e64 v37, 0, v213, s[0:1]
	v_sub_f32_e32 v36, v36, v37
	v_add_f32_e32 v86, v85, v36
	ds_write_b32 v42, v86
	s_waitcnt lgkmcnt(0)
	s_barrier
	ds_read2st64_b32 v[38:39], v43 offset1:2
	ds_read2st64_b32 v[36:37], v43 offset0:4 offset1:6
	s_waitcnt lgkmcnt(1)
	v_add_f32_e32 v88, v38, v39
	s_waitcnt lgkmcnt(0)
	v_add_f32_e32 v37, v36, v37
	v_add_f32_e32 v37, v88, v37
	s_and_saveexec_b64 s[0:1], s[38:39]
	s_cbranch_execz .LBB0_598
	v_mul_f32_e32 v88, 0x3fb8aa3b, v37
	v_exp_f32_e32 v88, v88
	ds_write_b32 v44, v88
	v_mul_f32_e32 v40, v40, v88
	s_branch .LBB0_598
